# one static s_setprio 1 for waves 4-7 before each GEMM phase K-loop (reset at phase end)
# baseline (speedup 1.0000x reference)
.LBB0_378:
	s_lshl_b32 s65, s3, 6
	s_and_b32 s1, s1, 3
	v_or_b32_e32 v6, s65, v3
	v_lshlrev_b32_e32 v6, 7, v6
	s_lshl_b32 s3, s1, 5
	v_or_b32_e32 v8, v6, v192
	v_or_b32_e32 v9, v6, v193
	v_or_b32_e32 v6, s3, v3
	v_lshlrev_b32_e32 v6, 7, v6
	s_mov_b64 s[48:49], 0x80
	v_or_b32_e32 v10, v6, v192
	v_or_b32_e32 v11, v6, v193
	v_lshl_add_u64 v[6:7], v[4:5], 0, s[48:49]
	s_add_i32 m0, s79, 0x18000
	s_mov_b64 s[50:51], 0x40080
	s_waitcnt vmcnt(2)
	s_barrier
	global_load_lds_dwordx4 v[6:7], off
	v_lshl_add_u64 v[6:7], v[4:5], 0, s[50:51]
	s_add_i32 m0, s79, 0x1a000
	s_mov_b64 s[52:53], 0x10080
	global_load_lds_dwordx4 v[6:7], off
	v_lshl_add_u64 v[6:7], v[4:5], 0, s[52:53]
	s_add_i32 m0, s79, 0x1c000
	s_mov_b64 s[54:55], 0x50080
	global_load_lds_dwordx4 v[6:7], off
	v_lshl_add_u64 v[4:5], v[4:5], 0, s[54:55]
	s_add_i32 m0, s79, 0x1e000
	v_writelane_b32 v254, s34, 25
	global_load_lds_dwordx4 v[4:5], off
	s_nop 0
	v_writelane_b32 v254, s35, 26
	v_writelane_b32 v254, s26, 27
	s_cmpk_lt_u32 s0, 0x100
	v_or_b32_e32 v4, s3, v191
	v_writelane_b32 v254, s27, 28
	s_cselect_b64 s[56:57], -1, 0
	s_lshl_b32 s85, s1, 6
	s_ashr_i32 s3, s33, 31
	s_ashr_i32 s73, s2, 31
	v_readlane_b32 s0, v254, 13
	v_readlane_b32 s1, v254, 14
	s_add_u32 s58, s0, 0x783800
	s_addc_u32 s59, s1, 0
	s_add_u32 s60, s0, 0x784800
	s_mov_b32 s13, 0x14800
	s_addc_u32 s61, s1, 0
	s_addk_i32 s13, 0x100
	s_mov_b32 s12, 0x10800
	v_add_u32_e32 v205, s13, v10
	v_add_u32_e32 v206, s13, v11
	s_mov_b32 s13, 0x18800
	s_addk_i32 s12, 0x100
	s_addk_i32 s13, 0x100
	s_mov_b32 s8, 0x18000
	s_mov_b32 s9, 0x1c000
	s_waitcnt vmcnt(4)
	s_mov_b32 s1, 0x10000
	v_add_u32_e32 v201, s12, v10
	v_add_u32_e32 v202, s12, v11
	s_mov_b32 s12, 0x14000
	v_add_u32_e32 v209, s13, v10
	v_add_u32_e32 v210, s13, v11
	s_mov_b32 s13, 0x1c800
	v_lshlrev_b32_e32 v160, 1, v191
	s_addk_i32 s1, 0x100
	s_addk_i32 s12, 0x100
	s_addk_i32 s13, 0x100
	s_movk_i32 s68, 0xfc40
	s_movk_i32 s92, 0xa040
	s_add_i32 s70, s8, 0x100
	s_add_i32 s71, s9, 0x100
	v_or_b32_e32 v198, 0xfffff900, v4
	v_cmp_gt_u32_e64 s[6:7], 8, v3
	v_lshl_add_u64 v[162:163], s[42:43], 0, v[160:161]
	v_lshl_add_u64 v[164:165], s[34:35], 0, v[160:161]
	v_lshl_add_u64 v[166:167], s[26:27], 0, v[160:161]
	v_add_u32_e32 v168, v194, v186
	v_mov_b32_e32 v169, v161
	s_mov_b32 s0, 0
	v_mov_b64_e32 v[170:171], 0x580
	v_mov_b64_e32 v[172:173], 0x57f
	v_add_u32_e32 v199, s1, v10
	v_add_u32_e32 v200, s1, v11
	v_add_u32_e32 v203, s12, v10
	v_add_u32_e32 v204, s12, v11
	v_add_u32_e32 v207, 0x100, v8
	v_add_u32_e32 v208, 0x100, v9
	v_add_u32_e32 v211, s13, v10
	v_add_u32_e32 v212, s13, v11
	s_movk_i32 s13, 0xc00
	s_mov_b32 s69, -1
	s_mov_b32 s72, 0x3e000000
	s_mov_b32 s93, -1
	v_add_u32_e32 v213, s70, v10
	v_add_u32_e32 v214, s70, v11
	v_add_u32_e32 v215, s71, v10
	v_add_u32_e32 v216, s71, v11
	v_readfirstlane_b32 s101, v156
	s_nop 0
	s_cmpk_lt_u32 s101, 0x100
	s_cbranch_scc1 .Lprio_skip_p1
	s_setprio 1
.Lprio_skip_p1:
	s_barrier
	s_branch .LBB0_381

.LBB0_490:
	s_setprio 0
	s_waitcnt vmcnt(0)
	v_readlane_b32 s26, v254, 27
	v_readlane_b32 s34, v254, 25
	s_mov_b32 s85, s95
	v_readlane_b32 s86, v254, 17
	v_readlane_b32 s39, v254, 24
	v_readlane_b32 s27, v254, 28
	v_readlane_b32 s35, v254, 26
	s_barrier

.LBB0_765:
	s_mov_b64 s[24:25], 0x80
	v_lshl_add_u64 v[10:11], v[6:7], 0, s[24:25]
	s_add_i32 m0, s66, 0x18000
	s_mov_b64 s[50:51], 0x60080
	s_waitcnt vmcnt(2)
	s_barrier
	global_load_lds_dwordx4 v[10:11], off
	v_lshl_add_u64 v[10:11], v[6:7], 0, s[50:51]
	s_add_i32 m0, s66, 0x1a000
	s_mov_b64 s[52:53], 0x18080
	global_load_lds_dwordx4 v[10:11], off
	v_lshl_add_u64 v[10:11], v[6:7], 0, s[52:53]
	s_add_i32 m0, s66, 0x1c000
	s_mov_b64 s[54:55], 0x78080
	global_load_lds_dwordx4 v[10:11], off
	v_lshl_add_u64 v[6:7], v[6:7], 0, s[54:55]
	s_add_i32 m0, s66, 0x1e000
	s_and_b32 s0, s0, 3
	global_load_lds_dwordx4 v[6:7], off
	v_lshl_or_b32 v9, s0, 12, v172
	v_or_b32_e32 v159, v9, v192
	v_or_b32_e32 v173, v9, v193
	v_cmp_gt_u32_e64 s[8:9], 8, v3
	v_mov_b32_e32 v9, 0xffffc040
	v_lshl_or_b32 v1, s1, 6, v3
	v_cndmask_b32_e64 v148, v9, 0, s[8:9]
	v_mov_b32_e32 v9, 0x4040
	s_lshl_b32 s0, s0, 6
	v_cndmask_b32_e64 v150, 0, v9, s[8:9]
	v_lshlrev_b32_e32 v9, 10, v1
	s_cmpk_lt_u32 s10, 0x100
	v_or_b32_e32 v174, s0, v191
	v_or3_b32 v175, v191, v9, s0
	s_mov_b32 s0, 0x10000
	s_cselect_b64 s[56:57], -1, 0
	s_add_i32 s73, s0, 0x100
	s_mov_b32 s0, 0x10800
	s_add_i32 s77, s0, 0x100
	s_mov_b32 s0, 0x14000
	s_add_i32 s79, s0, 0x100
	s_mov_b32 s0, 0x14800
	v_lshlrev_b32_e32 v6, 7, v1
	s_waitcnt vmcnt(4)
	s_add_i32 s80, s0, 0x100
	s_mov_b32 s0, 0x18800
	v_or_b32_e32 v7, v6, v192
	v_or_b32_e32 v6, v6, v193
	s_mov_b32 s1, 0x18000
	s_mov_b32 s11, 0x1c000
	v_and_b32_e32 v4, 7, v4
	v_lshlrev_b32_e32 v8, 1, v8
	s_add_i32 s81, s0, 0x100
	s_mov_b32 s0, 0x1c800
	s_movk_i32 s58, 0xc040
	s_mov_b32 s70, 0
	v_cndmask_b32_e64 v149, -1, 0, s[8:9]
	v_mov_b32_e32 v151, v5
	s_ashr_i32 s71, s33, 31
	s_ashr_i32 s72, s2, 31
	v_lshl_add_u32 v152, v4, 4, v8
	v_mov_b32_e32 v153, v5
	v_mov_b64_e32 v[154:155], 0x100
	v_mov_b64_e32 v[160:161], 0xff
	v_add_u32_e32 v176, 0x100, v7
	v_add_u32_e32 v177, 0x100, v6
	s_add_i32 s82, s0, 0x100
	s_mov_b32 s59, -1
	s_mov_b64 s[60:61], 0x4040
	s_add_i32 s83, s1, 0x100
	s_add_i32 s84, s11, 0x100
	v_mov_b64_e32 v[162:163], 0x40000
	v_mov_b64_e32 v[164:165], 0x48000
	v_mov_b64_e32 v[166:167], 0x50000
	v_mov_b64_e32 v[168:169], 0x58000
	v_readfirstlane_b32 s101, v156
	s_nop 0
	s_cmpk_lt_u32 s101, 0x100
	s_cbranch_scc1 .Lprio_skip_p3
	s_setprio 1

.LBB0_803:
	s_setprio 0
	s_waitcnt vmcnt(0)
	s_barrier

.LBB0_964:
	s_mov_b64 s[36:37], 0x80
	v_lshl_add_u64 v[134:135], v[132:133], 0, s[36:37]
	s_add_i32 m0, s5, 0x18000
	s_mov_b64 s[44:45], 0x40080
	s_waitcnt vmcnt(2)
	s_barrier
	global_load_lds_dwordx4 v[134:135], off
	v_lshl_add_u64 v[134:135], v[132:133], 0, s[44:45]
	s_add_i32 m0, s5, 0x1a000
	s_mov_b64 s[46:47], 0x10080
	global_load_lds_dwordx4 v[134:135], off
	v_lshl_add_u64 v[134:135], v[132:133], 0, s[46:47]
	s_add_i32 m0, s5, 0x1c000
	s_mov_b64 s[50:51], 0x50080
	global_load_lds_dwordx4 v[134:135], off
	v_lshl_add_u64 v[132:133], v[132:133], 0, s[50:51]
	s_add_i32 m0, s5, 0x1e000
	s_cmpk_lt_u32 s39, 0x100
	global_load_lds_dwordx4 v[132:133], off
	v_or_b32_e32 v165, s12, v191
	s_mov_b32 s12, 0x10000
	v_or_b32_e32 v162, s52, v3
	s_cselect_b64 s[52:53], -1, 0
	s_add_i32 s72, s12, 0x100
	s_mov_b32 s12, 0x10800
	v_lshlrev_b32_e32 v132, 7, v162
	s_add_i32 s73, s12, 0x100
	s_mov_b32 s12, 0x14800
	v_or_b32_e32 v133, v132, v192
	v_or_b32_e32 v134, v132, v193
	v_lshl_or_b32 v132, s3, 12, v172
	s_waitcnt vmcnt(4)
	s_add_i32 s79, s12, 0x100
	s_mov_b32 s12, 0x18800
	v_or_b32_e32 v163, v132, v192
	v_or_b32_e32 v164, v132, v193
	s_mov_b32 s14, 0x18000
	s_mov_b32 s15, 0x1c000
	v_mov_b32_e32 v132, 0
	v_add_u32_e32 v166, 0x100, v133
	s_add_i32 s80, s12, 0x100
	s_mov_b32 s12, 0x1c800
	s_movk_i32 s56, 0xc040
	v_mbcnt_lo_u32_b32 v133, -1, 0
	v_cmp_gt_u32_e64 s[8:9], 8, v3
	s_mov_b32 s55, 0
	v_cmp_eq_u32_e64 s[10:11], 0, v190
	s_ashr_i32 s39, s2, 31
	v_add_u32_e32 v142, v194, v186
	v_mov_b32_e32 v143, v132
	s_add_i32 s77, s13, 0x100
	v_add_u32_e32 v167, 0x100, v134
	s_add_i32 s81, s12, 0x100
	s_mov_b32 s57, -1
	s_mov_b64 s[58:59], 0x4040
	v_mbcnt_hi_u32_b32 v168, -1, v133
	v_mov_b64_e32 v[144:145], 0x100
	v_mov_b64_e32 v[146:147], 0xff
	s_add_i32 s82, s14, 0x100
	s_add_i32 s83, s15, 0x100
	s_mov_b32 s84, 0
	v_readfirstlane_b32 s101, v156
	s_nop 0
	s_cmpk_lt_u32 s101, 0x100
	s_cbranch_scc1 .Lprio_skip_p4
	s_setprio 1

.LBB0_1013:
	s_setprio 0
	v_cndmask_b32_e64 v1, 0, 1, s[48:49]
	v_cmp_ne_u32_e64 s[8:9], 1, v1
	s_andn2_b64 vcc, exec, s[48:49]
	s_cbranch_vccnz .LBB0_1027
	s_waitcnt vmcnt(0)
	s_waitcnt vmcnt(0) lgkmcnt(0)
	s_barrier
	s_and_saveexec_b64 s[4:5], s[96:97]
	s_cbranch_execz .LBB0_1033
	s_mov_b64 s[12:13], exec
	v_mbcnt_lo_u32_b32 v1, s12, 0
	s_lshl_b32 s3, s2, 6
	v_mbcnt_hi_u32_b32 v1, s13, v1
	s_and_b32 s3, s3, 0x1c0
	v_cmp_eq_u32_e32 vcc, 0, v1
	s_and_saveexec_b64 s[10:11], vcc
	s_cbranch_execz .LBB0_1017
	s_lshl_b32 s14, s3, 2
	s_bcnt1_i32_b64 s15, s[12:13]
	s_getpc_b64 s[12:13]
	s_add_u32 s12, s12, g_ctl@rel32@lo+53252
	s_addc_u32 s13, s13, g_ctl@rel32@hi+53260
	v_mov_b32_e32 v4, s14
	v_mov_b32_e32 v5, s15
	global_atomic_add v4, v4, v5, s[12:13] sc0

.LBB0_1125:
	s_mov_b64 s[22:23], 0x80
	v_lshl_add_u64 v[6:7], v[4:5], 0, s[22:23]
	s_add_i32 m0, s34, 0x18000
	s_mov_b64 s[24:25], 0x40080
	s_waitcnt vmcnt(2)
	s_barrier
	global_load_lds_dwordx4 v[6:7], off
	v_lshl_add_u64 v[6:7], v[4:5], 0, s[24:25]
	s_add_i32 m0, s34, 0x1a000
	s_mov_b64 s[28:29], 0x10080
	global_load_lds_dwordx4 v[6:7], off
	v_lshl_add_u64 v[6:7], v[4:5], 0, s[28:29]
	s_add_i32 m0, s34, 0x1c000
	s_mov_b64 s[36:37], 0x50080
	global_load_lds_dwordx4 v[6:7], off
	v_lshl_add_u64 v[4:5], v[4:5], 0, s[36:37]
	s_add_i32 m0, s34, 0x1e000
	s_and_b32 s45, s4, 3
	global_load_lds_dwordx4 v[4:5], off
	s_cmpk_lt_u32 s10, 0x100
	s_cselect_b64 s[40:41], -1, 0
	s_lshl_b32 s10, s11, 8
	s_addk_i32 s10, 0x100
	s_add_i32 s10, s10, 0x27400
	v_lshl_or_b32 v6, s45, 12, v172
	v_lshl_add_u32 v143, v3, 2, s10
	s_mov_b32 s10, 0x10800
	v_or_b32_e32 v7, v6, v192
	v_or_b32_e32 v6, v6, v193
	s_addk_i32 s10, 0x100
	v_add_u32_e32 v147, s10, v7
	v_add_u32_e32 v148, s10, v6
	s_mov_b32 s10, 0x14800
	s_addk_i32 s10, 0x100
	v_add_u32_e32 v151, s10, v7
	v_add_u32_e32 v152, s10, v6
	s_mov_b32 s10, 0x18800
	v_lshl_or_b32 v142, s11, 6, v3
	s_addk_i32 s10, 0x100
	v_lshlrev_b32_e32 v4, 7, v142
	s_mov_b32 s56, 0x18000
	s_mov_b32 s57, 0x1c000
	s_waitcnt vmcnt(4)
	v_add_u32_e32 v155, s10, v7
	v_add_u32_e32 v160, s10, v6
	s_mov_b32 s10, 0x1c800
	v_or_b32_e32 v5, v4, v192
	v_or_b32_e32 v4, v4, v193
	v_lshl_or_b32 v144, s45, 6, v191
	s_mov_b32 s45, 0
	s_add_i32 s67, s46, 0x100
	s_add_i32 s72, s44, 0x100
	s_addk_i32 s10, 0x100
	s_mov_b32 s46, 0xffff0040
	s_add_i32 s73, s56, 0x100
	s_add_i32 s77, s57, 0x100
	v_cmp_gt_u32_e64 s[4:5], 8, v3
	s_ashr_i32 s65, s2, 31
	v_add_u32_e32 v132, v194, v186
	v_mov_b32_e32 v133, v159
	v_mov_b64_e32 v[134:135], 0x400
	v_mov_b64_e32 v[136:137], 0x3ff
	v_add_u32_e32 v145, s67, v7
	v_add_u32_e32 v146, s67, v6
	v_add_u32_e32 v149, s72, v7
	v_add_u32_e32 v150, s72, v6
	v_add_u32_e32 v153, 0x100, v5
	v_add_u32_e32 v154, 0x100, v4
	v_add_u32_e32 v161, s10, v7
	v_add_u32_e32 v162, s10, v6
	s_mov_b32 s47, -1
	s_mov_b64 s[48:49], 0x10040
	s_mov_b64 s[50:51], 0x130040
	s_mov_b64 s[52:53], 0x160000
	s_mov_b64 s[54:55], 0x150040
	v_add_u32_e32 v163, s73, v7
	v_add_u32_e32 v164, s73, v6
	v_add_u32_e32 v165, s77, v7
	v_add_u32_e32 v166, s77, v6
	s_mov_b32 s44, s45
	v_readfirstlane_b32 s101, v156
	s_nop 0
	s_cmpk_lt_u32 s101, 0x100
	s_cbranch_scc1 .Lprio_skip_p5
	s_setprio 1

.LBB0_1361:
	s_mov_b64 s[24:25], 0x80
	v_lshl_add_u64 v[8:9], v[4:5], 0, s[24:25]
	s_add_i32 m0, s35, 0x18000
	s_mov_b64 s[28:29], 0x100080
	s_waitcnt vmcnt(2)
	s_barrier
	global_load_lds_dwordx4 v[8:9], off
	v_lshl_add_u64 v[8:9], v[4:5], 0, s[28:29]
	s_add_i32 m0, s35, 0x1a000
	s_mov_b64 s[36:37], 0x40080
	global_load_lds_dwordx4 v[8:9], off
	v_lshl_add_u64 v[8:9], v[4:5], 0, s[36:37]
	s_add_i32 m0, s35, 0x1c000
	s_mov_b64 s[40:41], 0x140080
	global_load_lds_dwordx4 v[8:9], off
	v_lshl_add_u64 v[4:5], v[4:5], 0, s[40:41]
	s_add_i32 m0, s35, 0x1e000
	v_lshrrev_b32_e32 v142, 4, v157
	global_load_lds_dwordx4 v[4:5], off
	s_lshl_b32 s62, s4, 6
	v_or_b32_e32 v168, s62, v3
	v_xor_b32_e32 v5, v142, v187
	v_bitop3_b32 v7, v142, v187, 4 bitop3:0x36
	s_and_b32 s9, s1, 3
	v_lshlrev_b32_e32 v4, 7, v168
	v_lshlrev_b32_e32 v5, 4, v5
	v_lshlrev_b32_e32 v7, 4, v7
	v_or_b32_e32 v8, v4, v5
	v_or_b32_e32 v9, v4, v7
	v_lshl_or_b32 v4, s9, 12, v172
	s_add_i32 s66, s5, 0x100
	s_mov_b32 s5, 0x14800
	v_or_b32_e32 v144, v4, v7
	s_waitcnt vmcnt(4)
	v_add_u32_e32 v134, v6, v186
	v_mov_b32_e32 v6, v133
	v_mov_b32_e32 v7, v133
	s_add_i32 s67, s5, 0x100
	s_mov_b32 s5, 0x18800
	v_or_b32_e32 v143, v4, v5
	s_mov_b32 s4, 0x18000
	s_mov_b32 s7, 0x1c000
	v_mov_b32_e32 v4, v133
	v_mov_b32_e32 v5, v133
	s_add_i32 s64, s6, 0x100
	s_mov_b32 s6, 0x10800
	v_add_u32_e32 v145, 0x100, v8
	v_add_u32_e32 v146, 0x100, v9
	s_add_i32 s68, s5, 0x100
	s_mov_b32 s5, 0x1c800
	v_mov_b64_e32 v[10:11], v[6:7]
	v_mov_b64_e32 v[22:23], v[6:7]
	v_mov_b64_e32 v[26:27], v[6:7]
	v_mov_b64_e32 v[38:39], v[6:7]
	v_mov_b64_e32 v[42:43], v[6:7]
	v_mov_b64_e32 v[54:55], v[6:7]
	v_mov_b64_e32 v[58:59], v[6:7]
	v_mov_b64_e32 v[14:15], v[6:7]
	v_mov_b64_e32 v[18:19], v[6:7]
	v_mov_b64_e32 v[30:31], v[6:7]
	v_mov_b64_e32 v[34:35], v[6:7]
	v_mov_b64_e32 v[46:47], v[6:7]
	v_mov_b64_e32 v[50:51], v[6:7]
	v_mov_b64_e32 v[62:63], v[6:7]
	v_mov_b64_e32 v[66:67], v[6:7]
	v_mov_b64_e32 v[70:71], v[6:7]
	v_mov_b64_e32 v[74:75], v[6:7]
	v_mov_b64_e32 v[86:87], v[6:7]
	v_mov_b64_e32 v[90:91], v[6:7]
	v_mov_b64_e32 v[102:103], v[6:7]
	v_mov_b64_e32 v[106:107], v[6:7]
	v_mov_b64_e32 v[118:119], v[6:7]
	v_mov_b64_e32 v[122:123], v[6:7]
	v_mov_b64_e32 v[78:79], v[6:7]
	v_mov_b64_e32 v[82:83], v[6:7]
	v_mov_b64_e32 v[94:95], v[6:7]
	v_mov_b64_e32 v[98:99], v[6:7]
	v_mov_b64_e32 v[110:111], v[6:7]
	v_mov_b64_e32 v[114:115], v[6:7]
	v_mov_b64_e32 v[126:127], v[6:7]
	v_mov_b64_e32 v[130:131], v[6:7]
	s_sext_i32_i8 s0, s0
	v_mov_b32_e32 v135, v133
	s_mov_b32 s63, 0
	v_mov_b64_e32 v[136:137], 0x100
	v_mov_b64_e32 v[138:139], 0xff
	s_add_i32 s65, s6, 0x100
	s_mov_b64 s[44:45], 0x80080
	s_mov_b64 s[46:47], 0x180080
	s_add_i32 s69, s5, 0x100
	s_add_i32 s70, s4, 0x100
	s_add_i32 s71, s7, 0x100
	v_mov_b64_e32 v[8:9], v[4:5]
	v_mov_b64_e32 v[20:21], v[4:5]
	v_mov_b64_e32 v[24:25], v[4:5]
	v_mov_b64_e32 v[36:37], v[4:5]
	v_mov_b64_e32 v[40:41], v[4:5]
	v_mov_b64_e32 v[52:53], v[4:5]
	v_mov_b64_e32 v[56:57], v[4:5]
	v_mov_b64_e32 v[12:13], v[4:5]
	v_mov_b64_e32 v[16:17], v[4:5]
	v_mov_b64_e32 v[28:29], v[4:5]
	v_mov_b64_e32 v[32:33], v[4:5]
	v_mov_b64_e32 v[44:45], v[4:5]
	v_mov_b64_e32 v[48:49], v[4:5]
	v_mov_b64_e32 v[60:61], v[4:5]
	v_mov_b64_e32 v[64:65], v[4:5]
	v_mov_b64_e32 v[68:69], v[4:5]
	v_mov_b64_e32 v[72:73], v[4:5]
	v_mov_b64_e32 v[84:85], v[4:5]
	v_mov_b64_e32 v[88:89], v[4:5]
	v_mov_b64_e32 v[100:101], v[4:5]
	v_mov_b64_e32 v[104:105], v[4:5]
	v_mov_b64_e32 v[116:117], v[4:5]
	v_mov_b64_e32 v[120:121], v[4:5]
	v_mov_b64_e32 v[76:77], v[4:5]
	v_mov_b64_e32 v[80:81], v[4:5]
	v_mov_b64_e32 v[92:93], v[4:5]
	v_mov_b64_e32 v[96:97], v[4:5]
	v_mov_b64_e32 v[108:109], v[4:5]
	v_mov_b64_e32 v[112:113], v[4:5]
	v_mov_b64_e32 v[124:125], v[4:5]
	v_mov_b64_e32 v[128:129], v[4:5]
	v_readfirstlane_b32 s101, v156
	s_nop 0
	s_cmpk_lt_u32 s101, 0x100
	s_cbranch_scc1 .Lprio_skip_p6
	s_setprio 1

.LBB0_1374:
	s_setprio 0
	s_waitcnt vmcnt(0)
	s_cmpk_gt_u32 s38, 0xff
	s_cbranch_scc1 .LBB0_1376
	s_barrier
